# attention queue ticket: return consumed at the unit-end hand-over behind a counted wait instead of right behind the atomic
# baseline (speedup 1.0000x reference)
.LBB0_1113:
	v_mov_b32_e32 v16, 0
	v_cmp_eq_u32_e64 s[22:23], 0, v230
	s_and_saveexec_b64 s[24:25], s[22:23]
	s_cbranch_execz .LBB0_1117
	s_mov_b64 s[72:73], exec
	v_mbcnt_lo_u32_b32 v2, s72, 0
	v_mbcnt_hi_u32_b32 v2, s73, v2
	v_cmp_eq_u32_e32 vcc, 0, v2
	s_and_saveexec_b64 s[70:71], vcc
	s_cbranch_execz .LBB0_1116
	s_bcnt1_i32_b64 s28, s[72:73]
	v_mov_b32_e32 v252, s28
	global_atomic_add v252, v3, v252, s[68:69] offset:256 sc0
.LBB0_1116:
	s_or_b64 exec, exec, s[70:71]
.LBB0_1117:
	s_or_b64 exec, exec, s[24:25]
	v_add_u32_e32 v2, s88, v232
	ds_read_b64_tr_b16 v[178:179], v2 offset:24576
	ds_read_b64_tr_b16 v[180:181], v2 offset:25088
	v_add_f32_e32 v4, v98, v99
	v_add_f32_e32 v4, v100, v4
	v_add_f32_e32 v4, v101, v4
	v_add_f32_e32 v4, v102, v4
	v_add_f32_e32 v4, v103, v4
	v_cvt_pk_bf16_f32 v142, v98, v99
	v_cvt_pk_bf16_f32 v143, v100, v101
	s_waitcnt lgkmcnt(9)
	v_mfma_f32_32x32x16_bf16 v[82:97], v[174:177], v[130:133], v[82:97]
	ds_read_b64_tr_b16 v[174:175], v2 offset:28672
	ds_read_b64_tr_b16 v[176:177], v2 offset:29184
	s_waitcnt lgkmcnt(10)
	v_mfma_f32_32x32x16_bf16 v[50:65], v[166:169], v[130:133], v[50:65]
	v_add_f32_e32 v4, v104, v4
	v_add_f32_e32 v4, v105, v4
	v_add_f32_e32 v4, v106, v4
	v_add_f32_e32 v4, v107, v4
	v_cvt_pk_bf16_f32 v144, v102, v103
	v_cvt_pk_bf16_f32 v145, v104, v105
	ds_read_b64_tr_b16 v[166:167], v2 offset:25600
	ds_read_b64_tr_b16 v[168:169], v2 offset:26112
	v_add_f32_e32 v4, v108, v4
	v_add_f32_e32 v4, v109, v4
	v_add_f32_e32 v4, v110, v4
	v_add_f32_e32 v4, v111, v4
	v_cvt_pk_bf16_f32 v138, v106, v107
	v_cvt_pk_bf16_f32 v139, v108, v109
	s_waitcnt lgkmcnt(11)
	v_mfma_f32_32x32x16_bf16 v[82:97], v[170:173], v[126:129], v[82:97]
	ds_read_b64_tr_b16 v[130:131], v2 offset:29696
	ds_read_b64_tr_b16 v[132:133], v2 offset:30208
	s_waitcnt lgkmcnt(12)
	v_mfma_f32_32x32x16_bf16 v[50:65], v[158:161], v[126:129], v[50:65]
	v_add_f32_e32 v4, v112, v4
	v_add_f32_e32 v4, v113, v4
	v_add_f32_e32 v4, v66, v4
	v_add_f32_e32 v4, v67, v4
	v_cvt_pk_bf16_f32 v140, v110, v111
	v_cvt_pk_bf16_f32 v141, v112, v113
	ds_read_b64_tr_b16 v[126:127], v2 offset:26624
	ds_read_b64_tr_b16 v[128:129], v2 offset:27136
	v_add_f32_e32 v4, v68, v4
	v_add_f32_e32 v4, v69, v4
	v_add_f32_e32 v4, v70, v4
	v_add_f32_e32 v4, v71, v4
	v_cvt_pk_bf16_f32 v134, v66, v67
	v_cvt_pk_bf16_f32 v135, v68, v69
	s_waitcnt lgkmcnt(13)
	v_mfma_f32_32x32x16_bf16 v[82:97], v[162:165], v[118:121], v[82:97]
	ds_read_b64_tr_b16 v[12:13], v2 offset:30720
	ds_read_b64_tr_b16 v[14:15], v2 offset:31232
	s_waitcnt lgkmcnt(14)
	v_mfma_f32_32x32x16_bf16 v[50:65], v[150:153], v[118:121], v[50:65]
	v_add_f32_e32 v4, v72, v4
	v_add_f32_e32 v4, v73, v4
	v_add_f32_e32 v4, v74, v4
	v_add_f32_e32 v4, v75, v4
	v_cvt_pk_bf16_f32 v136, v70, v71
	v_cvt_pk_bf16_f32 v137, v72, v73
	ds_read_b64_tr_b16 v[8:9], v2 offset:27648
	ds_read_b64_tr_b16 v[10:11], v2 offset:28160
	v_add_f32_e32 v4, v76, v4
	v_add_f32_e32 v4, v77, v4
	v_add_f32_e32 v4, v78, v4
	v_add_f32_e32 v17, v79, v4
	v_cvt_pk_bf16_f32 v122, v74, v75
	v_cvt_pk_bf16_f32 v123, v76, v77
	s_waitcnt lgkmcnt(14)
	v_mfma_f32_32x32x16_bf16 v[82:97], v[154:157], v[114:117], v[82:97]
	ds_read_b64_tr_b16 v[4:5], v2 offset:31744
	ds_read_b64_tr_b16 v[6:7], v2 offset:32256
	v_mfma_f32_32x32x16_bf16 v[50:65], v[146:149], v[114:117], v[50:65]
	v_add_f32_e32 v2, v80, v17
	v_add_f32_e32 v2, v81, v2
	v_add_f32_e32 v2, 0, v2
	v_cvt_pk_bf16_f32 v124, v78, v79
	v_cvt_pk_bf16_f32 v125, v80, v81
	v_or_b32_e32 v66, 0xe0, v224
	v_or_b32_e32 v17, 0xc0, v224
	v_cmp_le_i32_e32 vcc, v66, v229
	v_add_f32_e32 v2, v233, v2
	s_nop 2
	v_cndmask_b32_e32 v50, v218, v50, vcc
	v_cmp_lt_i32_e32 vcc, v17, v229
	s_nop 1
	v_cndmask_b32_e32 v67, v218, v83, vcc
	v_cmp_le_i32_e32 vcc, v17, v229
	v_or_b32_e32 v17, 0xe1, v224
	s_nop 0
	v_cndmask_b32_e32 v66, v218, v82, vcc
	v_cmp_le_i32_e32 vcc, v17, v229
	v_or_b32_e32 v17, 0xc2, v224
	v_max_f32_e32 v82, v66, v66
	v_cndmask_b32_e32 v51, v218, v51, vcc
	v_cmp_le_i32_e32 vcc, v17, v229
	v_or_b32_e32 v17, 0xe2, v224
	s_nop 0
	v_cndmask_b32_e32 v68, v218, v84, vcc
	v_cmp_le_i32_e32 vcc, v17, v229
	v_or_b32_e32 v17, 0xc3, v224
	s_nop 0
	v_cndmask_b32_e32 v52, v218, v52, vcc
	v_cmp_le_i32_e32 vcc, v17, v229
	v_or_b32_e32 v17, 0xe3, v224
	s_nop 0
	v_cndmask_b32_e32 v69, v218, v85, vcc
	v_cmp_le_i32_e32 vcc, v17, v229
	v_or_b32_e32 v17, 0xc8, v224
	s_nop 0
	v_cndmask_b32_e32 v53, v218, v53, vcc
	v_cmp_le_i32_e32 vcc, v17, v229
	v_or_b32_e32 v17, 0xe8, v224
	s_nop 0
	v_cndmask_b32_e32 v70, v218, v86, vcc
	v_cmp_le_i32_e32 vcc, v17, v229
	v_or_b32_e32 v17, 0xc9, v224
	s_nop 0
	v_cndmask_b32_e32 v54, v218, v54, vcc
	v_cmp_le_i32_e32 vcc, v17, v229
	v_or_b32_e32 v17, 0xe9, v224
	s_nop 0
	v_cndmask_b32_e32 v71, v218, v87, vcc
	v_cmp_le_i32_e32 vcc, v17, v229
	v_or_b32_e32 v17, 0xca, v224
	s_nop 0
	v_cndmask_b32_e32 v55, v218, v55, vcc
	v_cmp_le_i32_e32 vcc, v17, v229
	v_or_b32_e32 v17, 0xea, v224
	s_nop 0
	v_cndmask_b32_e32 v72, v218, v88, vcc
	v_cmp_le_i32_e32 vcc, v17, v229
	v_or_b32_e32 v17, 0xcb, v224
	s_nop 0
	v_cndmask_b32_e32 v56, v218, v56, vcc
	v_cmp_le_i32_e32 vcc, v17, v229
	v_or_b32_e32 v17, 0xeb, v224
	s_nop 0
	v_cndmask_b32_e32 v73, v218, v89, vcc
	v_cmp_le_i32_e32 vcc, v17, v229
	v_or_b32_e32 v17, 0xd0, v224
	s_nop 0
	v_cndmask_b32_e32 v57, v218, v57, vcc
	v_cmp_le_i32_e32 vcc, v17, v229
	v_or_b32_e32 v17, 0xf0, v224
	s_nop 0
	v_cndmask_b32_e32 v74, v218, v90, vcc
	v_cmp_le_i32_e32 vcc, v17, v229
	v_or_b32_e32 v17, 0xd1, v224
	s_nop 0
	v_cndmask_b32_e32 v58, v218, v58, vcc
	v_cmp_le_i32_e32 vcc, v17, v229
	v_or_b32_e32 v17, 0xf1, v224
	s_nop 0
	v_cndmask_b32_e32 v75, v218, v91, vcc
	v_cmp_le_i32_e32 vcc, v17, v229
	v_or_b32_e32 v17, 0xd2, v224
	s_nop 0
	v_cndmask_b32_e32 v59, v218, v59, vcc
	v_cmp_le_i32_e32 vcc, v17, v229
	v_or_b32_e32 v17, 0xf2, v224
	s_nop 0
	v_cndmask_b32_e32 v76, v218, v92, vcc
	v_cmp_le_i32_e32 vcc, v17, v229
	v_or_b32_e32 v17, 0xd3, v224
	s_nop 0
	v_cndmask_b32_e32 v60, v218, v60, vcc
	v_cmp_le_i32_e32 vcc, v17, v229
	v_or_b32_e32 v17, 0xf3, v224
	s_nop 0
	v_cndmask_b32_e32 v77, v218, v93, vcc
	v_cmp_le_i32_e32 vcc, v17, v229
	v_or_b32_e32 v17, 0xd8, v224
	s_nop 0
	v_cndmask_b32_e32 v61, v218, v61, vcc
	v_cmp_le_i32_e32 vcc, v17, v229
	v_or_b32_e32 v17, 0xf8, v224
	s_nop 0
	v_cndmask_b32_e32 v78, v218, v94, vcc
	v_cmp_le_i32_e32 vcc, v17, v229
	v_or_b32_e32 v17, 0xd9, v224
	s_nop 0
	v_cndmask_b32_e32 v62, v218, v62, vcc
	v_cmp_le_i32_e32 vcc, v17, v229
	v_or_b32_e32 v17, 0xf9, v224
	s_nop 0
	v_cndmask_b32_e32 v79, v218, v95, vcc
	v_cmp_le_i32_e32 vcc, v17, v229
	v_or_b32_e32 v17, 0xda, v224
	s_nop 0
	v_cndmask_b32_e32 v63, v218, v63, vcc
	v_cmp_le_i32_e32 vcc, v17, v229
	v_or_b32_e32 v17, 0xfa, v224
	s_nop 0
	v_cndmask_b32_e32 v80, v218, v96, vcc
	v_cmp_le_i32_e32 vcc, v17, v229
	v_or_b32_e32 v17, 0xdb, v224
	s_nop 0
	v_cndmask_b32_e32 v64, v218, v64, vcc
	v_cmp_le_i32_e32 vcc, v17, v229
	v_or_b32_e32 v17, 0xfb, v224
	s_nop 0
	v_cndmask_b32_e32 v81, v218, v97, vcc
	v_cmp_le_i32_e32 vcc, v17, v229
	v_max_f32_e32 v17, v67, v67
	v_max_f32_e32 v17, v82, v17
	v_max3_f32 v82, v68, v69, v51
	v_max3_f32 v17, v17, v50, v52
	v_max3_f32 v17, v17, v53, v70
	v_max3_f32 v82, v82, v72, v73
	v_max3_f32 v17, v17, v71, v54
	v_max3_f32 v82, v82, v56, v57
	v_max3_f32 v17, v17, v55, v74
	v_max3_f32 v82, v82, v76, v77
	v_max3_f32 v17, v17, v75, v58
	v_max3_f32 v82, v82, v60, v61
	v_cndmask_b32_e32 v65, v218, v65, vcc
	v_max3_f32 v17, v17, v59, v78
	v_max3_f32 v82, v82, v80, v81
	v_max3_f32 v17, v17, v79, v62
	v_max3_f32 v82, v82, v64, v65
	v_max3_f32 v17, v17, v63, v82
	v_mov_b32_e32 v82, v17
	s_nop 1
	v_permlane32_swap_b32_e32 v17, v82
	v_max_f32_e32 v82, v82, v82
	v_max_f32_e32 v17, v17, v17
	v_max_f32_e32 v17, v17, v82
	v_cmp_lt_f32_e32 vcc, s81, v17
	s_cmp_lg_u64 vcc, 0
	s_cselect_b64 s[24:25], -1, 0
	s_cbranch_vccnz .LBB0_1174

.LBB0_1120:
	v_add_f32_e32 v4, v66, v67
	v_add_f32_e32 v4, v68, v4
	v_add_f32_e32 v4, v69, v4
	v_add_f32_e32 v4, v70, v4
	v_add_f32_e32 v4, v71, v4
	v_add_f32_e32 v4, v72, v4
	v_add_f32_e32 v4, v73, v4
	v_add_f32_e32 v4, v74, v4
	v_add_f32_e32 v4, v75, v4
	v_add_f32_e32 v4, v76, v4
	v_add_f32_e32 v4, v77, v4
	v_add_f32_e32 v4, v78, v4
	v_add_f32_e32 v4, v79, v4
	v_add_f32_e32 v4, v80, v4
	v_add_f32_e32 v4, v81, v4
	v_add_f32_e32 v4, v4, v50
	v_add_f32_e32 v4, v51, v4
	v_add_f32_e32 v4, v52, v4
	v_add_f32_e32 v4, v53, v4
	v_add_f32_e32 v4, v54, v4
	v_add_f32_e32 v4, v55, v4
	v_add_f32_e32 v4, v56, v4
	v_add_f32_e32 v4, v57, v4
	v_add_f32_e32 v4, v58, v4
	v_add_f32_e32 v4, v59, v4
	v_add_f32_e32 v4, v60, v4
	v_add_f32_e32 v4, v61, v4
	v_add_f32_e32 v4, v62, v4
	v_add_f32_e32 v4, v63, v4
	v_add_f32_e32 v4, v64, v4
	v_add_f32_e32 v4, v65, v4
	v_add_f32_e32 v2, v2, v4
	v_cvt_pk_bf16_f32 v4, v66, v67
	v_cvt_pk_bf16_f32 v5, v68, v69
	v_cvt_pk_bf16_f32 v6, v70, v71
	v_cvt_pk_bf16_f32 v7, v72, v73
	v_cvt_pk_bf16_f32 v8, v74, v75
	v_cvt_pk_bf16_f32 v9, v76, v77
	v_cvt_pk_bf16_f32 v10, v78, v79
	v_cvt_pk_bf16_f32 v11, v80, v81
	v_cvt_pk_bf16_f32 v12, v50, v51
	v_cvt_pk_bf16_f32 v13, v52, v53
	v_cvt_pk_bf16_f32 v14, v54, v55
	v_cvt_pk_bf16_f32 v15, v56, v57
	v_cvt_pk_bf16_f32 v50, v58, v59
	v_cvt_pk_bf16_f32 v51, v60, v61
	v_cvt_pk_bf16_f32 v52, v62, v63
	v_cvt_pk_bf16_f32 v53, v64, v65
	s_cmp_lg_u32 0, -1
	s_cselect_b32 s24, 0, 0
	s_addk_i32 s24, 0x6000
	v_add3_u32 v17, v225, s24, v223
	v_add3_u32 v17, v17, v226, s87
	ds_read_b64_tr_b16 v[54:55],v17 offset:0
	ds_read_b64_tr_b16 v[56:57],v17 offset:512
	ds_read_b64_tr_b16 v[58:59],v17 offset:1024
	ds_read_b64_tr_b16 v[60:61],v17 offset:1536
	ds_read_b64_tr_b16 v[62:63],v17 offset:2048
	ds_read_b64_tr_b16 v[64:65],v17 offset:2560
	ds_read_b64_tr_b16 v[66:67],v17 offset:3072
	ds_read_b64_tr_b16 v[68:69],v17 offset:3584
	s_waitcnt lgkmcnt(0)
	s_nop 0
	v_mfma_f32_32x32x16_bf16 v[34:49], v[4:7], v[54:57], v[34:49]
	ds_read_b64_tr_b16 v[54:55],v17 offset:4096
	ds_read_b64_tr_b16 v[56:57],v17 offset:4608
	v_mfma_f32_32x32x16_bf16 v[34:49], v[8:11], v[58:61], v[34:49]
	ds_read_b64_tr_b16 v[58:59],v17 offset:5120
	ds_read_b64_tr_b16 v[60:61],v17 offset:5632
	v_mfma_f32_32x32x16_bf16 v[34:49], v[12:15], v[62:65], v[34:49]
	ds_read_b64_tr_b16 v[62:63],v17 offset:6144
	ds_read_b64_tr_b16 v[64:65],v17 offset:6656
	ds_read_b64_tr_b16 v[70:71],v17 offset:7168
	ds_read_b64_tr_b16 v[72:73],v17 offset:7680
	s_waitcnt lgkmcnt(0)
	v_mfma_f32_32x32x16_bf16 v[34:49], v[50:53], v[66:69], v[34:49]
	v_mfma_f32_32x32x16_bf16 v[18:33], v[4:7], v[54:57], v[18:33]
	v_mov_b32_e32 v4, v2
	s_nop 1
	v_permlane32_swap_b32_e32 v2, v4
	v_cmp_gt_u32_e32 vcc, 32, v219
	v_mfma_f32_32x32x16_bf16 v[18:33], v[8:11], v[58:61], v[18:33]
	v_mfma_f32_32x32x16_bf16 v[18:33], v[12:15], v[62:65], v[18:33]
	v_mfma_f32_32x32x16_bf16 v[18:33], v[50:53], v[70:73], v[18:33]
	s_and_saveexec_b64 s[24:25], vcc
	v_add_f32_e32 v2, v2, v4
	ds_write_b32 v228, v2 offset:49280
	s_or_b64 exec, exec, s[24:25]
	s_waitcnt lgkmcnt(0)
	ds_read_b128 v[4:7], v227 offset:49280
	ds_read_b128 v[8:11], v227 offset:49312
	s_lshl_b32 s24, s82, 12
	s_add_i32 s24, s24, 0
	v_lshlrev_b32_e32 v53, 9, v222
	s_waitcnt lgkmcnt(1)
	v_rcp_f32_e32 v2, v4
	v_rcp_f32_e32 v12, v5
	v_lshlrev_b32_e32 v54, 1, v221
	v_add3_u32 v53, s24, v53, v54
	v_mul_f32_e32 v34, v34, v2
	v_mul_f32_e32 v2, v18, v2
	v_cvt_pk_bf16_f32 v2, v2, s0
	v_rcp_f32_e32 v13, v6
	v_rcp_f32_e32 v14, v7
	s_waitcnt lgkmcnt(0)
	v_rcp_f32_e32 v15, v8
	ds_read_b128 v[4:7], v227 offset:49344
	v_rcp_f32_e32 v17, v9
	v_rcp_f32_e32 v50, v10
	v_rcp_f32_e32 v51, v11
	ds_read_b128 v[8:11], v227 offset:49376
	v_lshlrev_b32_e32 v52, 7, v224
	ds_write_b16 v53, v2 offset:51264
	v_mul_f32_e32 v2, v35, v12
	v_cvt_pk_bf16_f32 v2, v2, s0
	v_add3_u32 v18, s24, v52, v54
	ds_write_b16 v18, v2 offset:51328
	v_mul_f32_e32 v2, v19, v12
	v_cvt_pk_bf16_f32 v2, v2, s0
	ds_write_b16 v18, v2 offset:51392
	v_mul_f32_e32 v2, v36, v13
	v_cvt_pk_bf16_f32 v2, v2, s0
	ds_write_b16 v18, v2 offset:51456
	v_mul_f32_e32 v2, v20, v13
	v_cvt_pk_bf16_f32 v2, v2, s0
	ds_write_b16 v18, v2 offset:51520
	v_mul_f32_e32 v2, v37, v14
	v_cvt_pk_bf16_f32 v2, v2, s0
	ds_write_b16 v18, v2 offset:51584
	v_mul_f32_e32 v2, v21, v14
	v_cvt_pk_bf16_f32 v2, v2, s0
	ds_write_b16 v18, v2 offset:51648
	v_mul_f32_e32 v2, v38, v15
	v_cvt_pk_bf16_f32 v2, v2, s0
	ds_write_b16 v18, v2 offset:52224
	v_mul_f32_e32 v2, v22, v15
	v_cvt_pk_bf16_f32 v2, v2, s0
	ds_write_b16 v18, v2 offset:52288
	v_mul_f32_e32 v2, v39, v17
	v_cvt_pk_bf16_f32 v2, v2, s0
	ds_write_b16 v18, v2 offset:52352
	v_mul_f32_e32 v2, v23, v17
	v_cvt_pk_bf16_f32 v2, v2, s0
	ds_write_b16 v18, v2 offset:52416
	v_mul_f32_e32 v2, v40, v50
	v_cvt_pk_bf16_f32 v2, v2, s0
	ds_write_b16 v18, v2 offset:52480
	v_mul_f32_e32 v2, v24, v50
	v_cvt_pk_bf16_f32 v2, v2, s0
	s_waitcnt lgkmcnt(13)
	v_rcp_f32_e32 v4, v4
	ds_write_b16 v18, v2 offset:52544
	v_mul_f32_e32 v2, v41, v51
	v_cvt_pk_bf16_f32 v2, v2, s0
	ds_write_b16 v18, v2 offset:52608
	v_mul_f32_e32 v2, v25, v51
	v_cvt_pk_bf16_f32 v2, v2, s0
	v_rcp_f32_e32 v5, v5
	ds_write_b16 v18, v2 offset:52672
	v_mul_f32_e32 v2, v42, v4
	v_cvt_pk_bf16_f32 v2, v2, s0
	ds_write_b16 v18, v2 offset:53248
	v_mul_f32_e32 v2, v26, v4
	v_cvt_pk_bf16_f32 v2, v2, s0
	v_rcp_f32_e32 v6, v6
	ds_write_b16 v18, v2 offset:53312
	v_mul_f32_e32 v2, v43, v5
	v_cvt_pk_bf16_f32 v2, v2, s0
	ds_write_b16 v18, v2 offset:53376
	v_mul_f32_e32 v2, v27, v5
	v_cvt_pk_bf16_f32 v2, v2, s0
	v_rcp_f32_e32 v7, v7
	ds_write_b16 v18, v2 offset:53440
	v_mul_f32_e32 v2, v44, v6
	v_cvt_pk_bf16_f32 v2, v2, s0
	ds_write_b16 v18, v2 offset:53504
	v_mul_f32_e32 v2, v28, v6
	v_cvt_pk_bf16_f32 v2, v2, s0
	s_waitcnt lgkmcnt(14)
	v_rcp_f32_e32 v8, v8
	ds_write_b16 v18, v2 offset:53568
	v_mul_f32_e32 v2, v45, v7
	v_cvt_pk_bf16_f32 v2, v2, s0
	ds_write_b16 v18, v2 offset:53632
	v_mul_f32_e32 v2, v29, v7
	v_cvt_pk_bf16_f32 v2, v2, s0
	v_rcp_f32_e32 v9, v9
	ds_write_b16 v18, v2 offset:53696
	v_mul_f32_e32 v2, v46, v8
	v_cvt_pk_bf16_f32 v2, v2, s0
	ds_write_b16 v18, v2 offset:54272
	v_mul_f32_e32 v2, v30, v8
	v_cvt_pk_bf16_f32 v2, v2, s0
	v_rcp_f32_e32 v10, v10
	ds_write_b16 v18, v2 offset:54336
	v_mul_f32_e32 v2, v47, v9
	v_cvt_pk_bf16_f32 v2, v2, s0
	ds_write_b16 v18, v2 offset:54400
	v_mul_f32_e32 v2, v31, v9
	v_cvt_pk_bf16_f32 v2, v2, s0
	v_rcp_f32_e32 v11, v11
	ds_write_b16 v18, v2 offset:54464
	v_mul_f32_e32 v2, v48, v10
	v_cvt_pk_bf16_f32 v2, v2, s0
	ds_write_b16 v18, v2 offset:54528
	v_mul_f32_e32 v2, v32, v10
	v_cvt_pk_bf16_f32 v2, v2, s0
	ds_write_b16 v18, v2 offset:54592
	v_mul_f32_e32 v2, v49, v11
	v_cvt_pk_bf16_f32 v2, v2, s0
	ds_write_b16 v18, v2 offset:54656
	v_mul_f32_e32 v2, v33, v11
	v_cvt_pk_bf16_f32 v2, v2, s0
	ds_write_b16 v18, v2 offset:54720
	v_lshlrev_b32_e32 v2, 1, v220
	v_cvt_pk_bf16_f32 v34, v34, s0
	v_and_b32_e32 v2, 0x70, v2
	ds_write_b16 v53, v34 offset:51200
	v_lshrrev_b32_e32 v17, 3, v219
	v_add_u32_e32 v18, s24, v2
	s_waitcnt lgkmcnt(0)
	v_lshl_add_u64 v[12:13], s[66:67], 0, v[2:3]
	v_lshl_add_u32 v2, v17, 7, v18
	v_or_b32_e32 v19, 8, v17
	ds_read_b128 v[4:7], v2 offset:51200
	v_lshl_add_u32 v8, v19, 7, v18
	ds_read_b128 v[8:11], v8 offset:51200
	v_lshlrev_b32_e32 v2, 11, v17
	v_lshl_add_u64 v[14:15], v[12:13], 0, v[2:3]
	v_lshlrev_b32_e32 v2, 11, v19
	s_waitcnt lgkmcnt(1)
	global_store_dwordx4 v[14:15], v[4:7], off
	s_nop 1
	v_lshl_add_u64 v[4:5], v[12:13], 0, v[2:3]
	v_or_b32_e32 v2, 16, v17
	s_waitcnt lgkmcnt(0)
	global_store_dwordx4 v[4:5], v[8:11], off
	v_lshl_add_u32 v4, v2, 7, v18
	v_or_b32_e32 v17, 24, v17
	ds_read_b128 v[4:7], v4 offset:51200
	v_lshl_add_u32 v8, v17, 7, v18
	ds_read_b128 v[8:11], v8 offset:51200
	v_lshlrev_b32_e32 v2, 11, v2
	v_lshl_add_u64 v[14:15], v[12:13], 0, v[2:3]
	v_lshlrev_b32_e32 v2, 11, v17
	s_waitcnt lgkmcnt(1)
	global_store_dwordx4 v[14:15], v[4:7], off
	s_nop 1
	v_lshl_add_u64 v[4:5], v[12:13], 0, v[2:3]
	s_waitcnt lgkmcnt(0)
	global_store_dwordx4 v[4:5], v[8:11], off
	s_and_saveexec_b64 s[24:25], s[22:23]
	s_cbranch_execz .LBB0_1082
	s_waitcnt vmcnt(4)
	v_mov_b32_e32 v2, s78
	ds_write_b32 v2, v252
	s_branch .LBB0_1082

	.amdhsa_kernel _Z9hymba_fwd4Args
		.amdhsa_group_segment_fixed_size 0
		.amdhsa_private_segment_fixed_size 0
		.amdhsa_kernarg_size 408
		.amdhsa_user_sgpr_count 2
		.amdhsa_user_sgpr_dispatch_ptr 0
		.amdhsa_user_sgpr_queue_ptr 0
		.amdhsa_user_sgpr_kernarg_segment_ptr 1
		.amdhsa_user_sgpr_dispatch_id 0
		.amdhsa_user_sgpr_kernarg_preload_length 0
		.amdhsa_user_sgpr_kernarg_preload_offset 0
		.amdhsa_user_sgpr_private_segment_size 0
		.amdhsa_uses_dynamic_stack 0
		.amdhsa_enable_private_segment 0
		.amdhsa_system_sgpr_workgroup_id_x 1
		.amdhsa_system_sgpr_workgroup_id_y 0
		.amdhsa_system_sgpr_workgroup_id_z 0
		.amdhsa_system_sgpr_workgroup_info 0
		.amdhsa_system_vgpr_workitem_id 0
		.amdhsa_next_free_vgpr 256
		.amdhsa_next_free_sgpr 102
		.amdhsa_accum_offset 256
		.amdhsa_reserve_vcc 1
		.amdhsa_float_round_mode_32 0
		.amdhsa_float_round_mode_16_64 0
		.amdhsa_float_denorm_mode_32 3
		.amdhsa_float_denorm_mode_16_64 3
		.amdhsa_dx10_clamp 1
		.amdhsa_ieee_mode 1
		.amdhsa_fp16_overflow 0
		.amdhsa_tg_split 0
		.amdhsa_exception_fp_ieee_invalid_op 0
		.amdhsa_exception_fp_denorm_src 0
		.amdhsa_exception_fp_ieee_div_zero 0
		.amdhsa_exception_fp_ieee_overflow 0
		.amdhsa_exception_fp_ieee_underflow 0
		.amdhsa_exception_fp_ieee_inexact 0
		.amdhsa_exception_int_div_zero 0
	.end_amdhsa_kernel

amdhsa.kernels:
  - .agpr_count:     0
    .args:
      - .offset:         0
        .size:           152
        .value_kind:     by_value
      - .offset:         152
        .size:           4
        .value_kind:     hidden_block_count_x
      - .offset:         156
        .size:           4
        .value_kind:     hidden_block_count_y
      - .offset:         160
        .size:           4
        .value_kind:     hidden_block_count_z
      - .offset:         164
        .size:           2
        .value_kind:     hidden_group_size_x
      - .offset:         166
        .size:           2
        .value_kind:     hidden_group_size_y
      - .offset:         168
        .size:           2
        .value_kind:     hidden_group_size_z
      - .offset:         170
        .size:           2
        .value_kind:     hidden_remainder_x
      - .offset:         172
        .size:           2
        .value_kind:     hidden_remainder_y
      - .offset:         174
        .size:           2
        .value_kind:     hidden_remainder_z
      - .offset:         192
        .size:           8
        .value_kind:     hidden_global_offset_x
      - .offset:         200
        .size:           8
        .value_kind:     hidden_global_offset_y
      - .offset:         208
        .size:           8
        .value_kind:     hidden_global_offset_z
      - .offset:         216
        .size:           2
        .value_kind:     hidden_grid_dims
      - .offset:         272
        .size:           4
        .value_kind:     hidden_dynamic_lds_size
    .group_segment_fixed_size: 0
    .kernarg_segment_align: 8
    .kernarg_segment_size: 408
    .language:       OpenCL C
    .language_version:
      - 2
      - 0
    .max_flat_workgroup_size: 512
    .name:           _Z9hymba_fwd4Args
    .private_segment_fixed_size: 0
    .sgpr_count:     108
    .sgpr_spill_count: 4
    .symbol:         _Z9hymba_fwd4Args.kd
    .uniform_work_group_size: 1
    .uses_dynamic_stack: false
    .vgpr_count:     256
    .vgpr_spill_count: 0
    .wavefront_size: 64
